# grid barrier: non-last workgroups poll the top-level generation word directly (one hop less)
# speedup vs baseline: 1.0102x; 1.0102x over previous
.LBB0_67:
	s_or_b64 exec, exec, s[14:15]
	v_cvt_f32_u32_e32 v4, v2
	s_waitcnt vmcnt(0)
	v_readfirstlane_b32 s3, v3
	v_sub_u32_e32 v3, 0, v2
	v_rcp_iflag_f32_e32 v4, v4
	v_add_u32_e32 v5, s3, v1
	v_mul_f32_e32 v4, 0x4f7ffffe, v4
	v_cvt_u32_f32_e32 v4, v4
	v_mul_lo_u32 v1, v3, v4
	v_mul_hi_u32 v1, v4, v1
	v_add_u32_e32 v1, v4, v1
	v_mul_hi_u32 v1, v5, v1
	v_mul_lo_u32 v3, v1, v2
	v_sub_u32_e32 v3, v5, v3
	v_add_u32_e32 v4, 1, v1
	v_cmp_ge_u32_e32 vcc, v3, v2
	s_nop 1
	v_cndmask_b32_e32 v1, v1, v4, vcc
	v_sub_u32_e32 v4, v3, v2
	v_cndmask_b32_e32 v3, v3, v4, vcc
	v_add_u32_e32 v4, 1, v1
	v_cmp_ge_u32_e32 vcc, v3, v2
	v_add_u32_e32 v3, 1, v5
	s_nop 0
	v_cndmask_b32_e32 v1, v1, v4, vcc
	v_mul_lo_u32 v4, v2, v1
	v_add_u32_e32 v2, v4, v2
	v_cmp_ne_u32_e32 vcc, v3, v2
	s_and_saveexec_b64 s[12:13], vcc
	s_xor_b64 s[12:13], exec, s[12:13]
	s_cbranch_execz .LBB0_81
	s_waitcnt lgkmcnt(0)
	v_mov_b32_e32 v0, 0
	s_add_u32 s16, s8, 0x3300
	s_addc_u32 s17, s9, 0
	s_nop 0
	global_load_dword v0, v0, s[16:17] sc1
	s_waitcnt vmcnt(0)
	v_cmp_eq_u32_e32 vcc, v0, v1
	s_and_saveexec_b64 s[14:15], vcc
	s_cbranch_execz .LBB0_80
	s_mov_b32 s3, 1
	s_mov_b64 s[18:19], 0
	v_mov_b32_e32 v0, 0
	s_branch .LBB0_71

.LBB0_230:
	s_or_b64 exec, exec, s[10:11]
	v_cvt_f32_u32_e32 v4, v2
	s_waitcnt vmcnt(0)
	v_readfirstlane_b32 s8, v3
	v_sub_u32_e32 v3, 0, v2
	v_rcp_iflag_f32_e32 v4, v4
	v_add_u32_e32 v5, s8, v1
	v_mul_f32_e32 v4, 0x4f7ffffe, v4
	v_cvt_u32_f32_e32 v4, v4
	v_mul_lo_u32 v1, v3, v4
	v_mul_hi_u32 v1, v4, v1
	v_add_u32_e32 v1, v4, v1
	v_mul_hi_u32 v1, v5, v1
	v_mul_lo_u32 v3, v1, v2
	v_sub_u32_e32 v3, v5, v3
	v_add_u32_e32 v4, 1, v1
	v_cmp_ge_u32_e32 vcc, v3, v2
	s_nop 1
	v_cndmask_b32_e32 v1, v1, v4, vcc
	v_sub_u32_e32 v4, v3, v2
	v_cndmask_b32_e32 v3, v3, v4, vcc
	v_add_u32_e32 v4, 1, v1
	v_cmp_ge_u32_e32 vcc, v3, v2
	v_add_u32_e32 v3, 1, v5
	s_nop 0
	v_cndmask_b32_e32 v1, v1, v4, vcc
	v_mul_lo_u32 v4, v2, v1
	v_add_u32_e32 v2, v4, v2
	v_cmp_ne_u32_e32 vcc, v3, v2
	s_and_saveexec_b64 s[8:9], vcc
	s_xor_b64 s[8:9], exec, s[8:9]
	s_cbranch_execz .LBB0_244
	s_waitcnt lgkmcnt(0)
	s_add_u32 s12, s4, 0x3300
	s_addc_u32 s13, s5, 0
	s_nop 0
	global_load_dword v0, v145, s[12:13] sc1
	s_waitcnt vmcnt(0)
	v_cmp_eq_u32_e32 vcc, v0, v1
	s_and_saveexec_b64 s[10:11], vcc
	s_cbranch_execz .LBB0_243
	s_mov_b32 s28, 1
	s_mov_b64 s[14:15], 0
	s_branch .LBB0_234

.LBB0_296:
	s_or_b64 exec, exec, s[14:15]
	v_cvt_f32_u32_e32 v4, v2
	s_waitcnt vmcnt(0)
	v_readfirstlane_b32 s12, v3
	v_sub_u32_e32 v3, 0, v2
	v_rcp_iflag_f32_e32 v4, v4
	v_add_u32_e32 v5, s12, v1
	v_mul_f32_e32 v4, 0x4f7ffffe, v4
	v_cvt_u32_f32_e32 v4, v4
	v_mul_lo_u32 v1, v3, v4
	v_mul_hi_u32 v1, v4, v1
	v_add_u32_e32 v1, v4, v1
	v_mul_hi_u32 v1, v5, v1
	v_mul_lo_u32 v3, v1, v2
	v_sub_u32_e32 v3, v5, v3
	v_add_u32_e32 v4, 1, v1
	v_cmp_ge_u32_e32 vcc, v3, v2
	s_nop 1
	v_cndmask_b32_e32 v1, v1, v4, vcc
	v_sub_u32_e32 v4, v3, v2
	v_cndmask_b32_e32 v3, v3, v4, vcc
	v_add_u32_e32 v4, 1, v1
	v_cmp_ge_u32_e32 vcc, v3, v2
	v_add_u32_e32 v3, 1, v5
	s_nop 0
	v_cndmask_b32_e32 v1, v1, v4, vcc
	v_mul_lo_u32 v4, v2, v1
	v_add_u32_e32 v2, v4, v2
	v_cmp_ne_u32_e32 vcc, v3, v2
	s_and_saveexec_b64 s[12:13], vcc
	s_xor_b64 s[12:13], exec, s[12:13]
	s_cbranch_execz .LBB0_310
	s_waitcnt lgkmcnt(0)
	s_add_u32 s16, s8, 0x3300
	s_addc_u32 s17, s9, 0
	s_nop 0
	global_load_dword v0, v145, s[16:17] sc1
	s_waitcnt vmcnt(0)
	v_cmp_eq_u32_e32 vcc, v0, v1
	s_and_saveexec_b64 s[14:15], vcc
	s_cbranch_execz .LBB0_309
	s_mov_b32 s34, 1
	s_mov_b64 s[18:19], 0
	s_branch .LBB0_300

.LBB0_723:
	s_or_b64 exec, exec, s[20:21]
	v_cvt_f32_u32_e32 v4, v2
	s_waitcnt vmcnt(0)
	v_readfirstlane_b32 s10, v3
	v_sub_u32_e32 v3, 0, v2
	v_rcp_iflag_f32_e32 v4, v4
	v_add_u32_e32 v5, s10, v1
	v_mul_f32_e32 v4, 0x4f7ffffe, v4
	v_cvt_u32_f32_e32 v4, v4
	v_mul_lo_u32 v1, v3, v4
	v_mul_hi_u32 v1, v4, v1
	v_add_u32_e32 v1, v4, v1
	v_mul_hi_u32 v1, v5, v1
	v_mul_lo_u32 v3, v1, v2
	v_sub_u32_e32 v3, v5, v3
	v_add_u32_e32 v4, 1, v1
	v_cmp_ge_u32_e32 vcc, v3, v2
	s_nop 1
	v_cndmask_b32_e32 v1, v1, v4, vcc
	v_sub_u32_e32 v4, v3, v2
	v_cndmask_b32_e32 v3, v3, v4, vcc
	v_add_u32_e32 v4, 1, v1
	v_cmp_ge_u32_e32 vcc, v3, v2
	v_add_u32_e32 v3, 1, v5
	s_nop 0
	v_cndmask_b32_e32 v1, v1, v4, vcc
	v_mul_lo_u32 v4, v2, v1
	v_add_u32_e32 v2, v4, v2
	v_cmp_ne_u32_e32 vcc, v3, v2
	s_and_saveexec_b64 s[10:11], vcc
	s_xor_b64 s[10:11], exec, s[10:11]
	s_cbranch_execz .LBB0_737
	s_waitcnt lgkmcnt(0)
	s_add_u32 s26, s6, 0x3300
	s_addc_u32 s27, s7, 0
	s_nop 0
	global_load_dword v0, v145, s[26:27] sc1
	s_waitcnt vmcnt(0)
	v_cmp_eq_u32_e32 vcc, v0, v1
	s_and_saveexec_b64 s[20:21], vcc
	s_cbranch_execz .LBB0_736
	s_mov_b32 s12, 1
	s_mov_b64 s[28:29], 0
	s_branch .LBB0_727

.LBB0_892:
	s_or_b64 exec, exec, s[16:17]
	v_cvt_f32_u32_e32 v4, v2
	s_waitcnt vmcnt(0)
	v_readfirstlane_b32 s10, v3
	v_sub_u32_e32 v3, 0, v2
	v_rcp_iflag_f32_e32 v4, v4
	v_add_u32_e32 v5, s10, v1
	v_mul_f32_e32 v4, 0x4f7ffffe, v4
	v_cvt_u32_f32_e32 v4, v4
	v_mul_lo_u32 v1, v3, v4
	v_mul_hi_u32 v1, v4, v1
	v_add_u32_e32 v1, v4, v1
	v_mul_hi_u32 v1, v5, v1
	v_mul_lo_u32 v3, v1, v2
	v_sub_u32_e32 v3, v5, v3
	v_add_u32_e32 v4, 1, v1
	v_cmp_ge_u32_e32 vcc, v3, v2
	s_nop 1
	v_cndmask_b32_e32 v1, v1, v4, vcc
	v_sub_u32_e32 v4, v3, v2
	v_cndmask_b32_e32 v3, v3, v4, vcc
	v_add_u32_e32 v4, 1, v1
	v_cmp_ge_u32_e32 vcc, v3, v2
	v_add_u32_e32 v3, 1, v5
	s_nop 0
	v_cndmask_b32_e32 v1, v1, v4, vcc
	v_mul_lo_u32 v4, v2, v1
	v_add_u32_e32 v2, v4, v2
	v_cmp_ne_u32_e32 vcc, v3, v2
	s_and_saveexec_b64 s[10:11], vcc
	s_xor_b64 s[10:11], exec, s[10:11]
	s_cbranch_execz .LBB0_906
	s_waitcnt lgkmcnt(0)
	s_add_u32 s28, s6, 0x3300
	s_addc_u32 s29, s7, 0
	s_nop 0
	global_load_dword v0, v145, s[28:29] sc1
	s_waitcnt vmcnt(0)
	v_cmp_eq_u32_e32 vcc, v0, v1
	s_and_saveexec_b64 s[16:17], vcc
	s_cbranch_execz .LBB0_905
	s_mov_b32 s12, 1
	s_mov_b64 s[30:31], 0
	s_branch .LBB0_896

.LBB0_1126:
	s_or_b64 exec, exec, s[22:23]
	v_cvt_f32_u32_e32 v4, v2
	s_waitcnt vmcnt(0)
	v_readfirstlane_b32 s12, v3
	v_sub_u32_e32 v3, 0, v2
	v_rcp_iflag_f32_e32 v4, v4
	v_add_u32_e32 v5, s12, v1
	v_mul_f32_e32 v4, 0x4f7ffffe, v4
	v_cvt_u32_f32_e32 v4, v4
	v_mul_lo_u32 v1, v3, v4
	v_mul_hi_u32 v1, v4, v1
	v_add_u32_e32 v1, v4, v1
	v_mul_hi_u32 v1, v5, v1
	v_mul_lo_u32 v3, v1, v2
	v_sub_u32_e32 v3, v5, v3
	v_add_u32_e32 v4, 1, v1
	v_cmp_ge_u32_e32 vcc, v3, v2
	s_nop 1
	v_cndmask_b32_e32 v1, v1, v4, vcc
	v_sub_u32_e32 v4, v3, v2
	v_cndmask_b32_e32 v3, v3, v4, vcc
	v_add_u32_e32 v4, 1, v1
	v_cmp_ge_u32_e32 vcc, v3, v2
	v_add_u32_e32 v3, 1, v5
	s_nop 0
	v_cndmask_b32_e32 v1, v1, v4, vcc
	v_mul_lo_u32 v4, v2, v1
	v_add_u32_e32 v2, v4, v2
	v_cmp_ne_u32_e32 vcc, v3, v2
	s_and_saveexec_b64 s[12:13], vcc
	s_xor_b64 s[16:17], exec, s[12:13]
	s_cbranch_execz .LBB0_1140
	s_waitcnt lgkmcnt(0)
	s_add_u32 s24, s6, 0x3300
	s_addc_u32 s25, s7, 0
	s_nop 0
	global_load_dword v0, v145, s[24:25] sc1
	s_waitcnt vmcnt(0)
	v_cmp_eq_u32_e32 vcc, v0, v1
	s_and_saveexec_b64 s[22:23], vcc
	s_cbranch_execz .LBB0_1139
	s_mov_b32 s12, 1
	s_mov_b64 s[26:27], 0
	s_branch .LBB0_1130
